# residual-GEMM tail strips: loads of four k-steps in flight instead of one load per wait
# speedup vs baseline: 1.0060x; 1.0026x over previous
; __device__ __forceinline__ void tail_resid(const bf16* __restrict__ A, const bf16* __restrict__ Bt, int K, unsigned char* ws, int slot, float amul, LAS unsigned char* lds, int lane, int wave) {
;     ...
;         const bf16* ap = A + (size_t)(MT0 + 16 * rs + fr) * K + wave * kw + 8 * fq;
;         const bf16* bp = Bt + (size_t)(64 * cs + fr) * K + wave * kw + 8 * fq;
;         f32x4 acc[4];
; #pragma unroll
;         for (int t = 0; t < 4; ++t) acc[t] = (f32x4){0.f, 0.f, 0.f, 0.f};
; #pragma unroll 4
;         for (int k0 = 0; k0 < kw; k0 += 32) {
;             const bf16x8 af = *(const bf16x8*)(ap + k0);
; #pragma unroll
;             for (int t = 0; t < 4; ++t) { const bf16x8 bf = *(const bf16x8*)(bp + (size_t)(16 * t) * K + k0); acc[t] = __builtin_amdgcn_mfma_f32_16x16x32_bf16(bf, af, acc[t], 0, 0, 0); }
;         }
.LBB0_1405:
	v_lshl_add_u64 v[32:33], v[32:33], 0, s[8:9]
	v_lshl_add_u64 v[34:35], v[34:35], 0, s[8:9]
	v_lshl_add_u64 v[36:37], v[36:37], 0, s[8:9]
	v_lshl_add_u64 v[38:39], v[38:39], 0, s[8:9]
	v_lshl_add_u64 v[40:41], v[40:41], 0, s[8:9]
	s_lshr_b32 s101, s16, 5
	s_add_i32 s15, s101, -4
	global_load_dwordx4 v[56:59], v[32:33], off
	global_load_dwordx4 v[60:63], v[34:35], off
	global_load_dwordx4 v[64:67], v[36:37], off
	global_load_dwordx4 v[68:71], v[38:39], off
	global_load_dwordx4 v[72:75], v[40:41], off
	v_lshl_add_u64 v[32:33], v[32:33], 0, 64
	v_lshl_add_u64 v[34:35], v[34:35], 0, 64
	v_lshl_add_u64 v[36:37], v[36:37], 0, 64
	v_lshl_add_u64 v[38:39], v[38:39], 0, 64
	v_lshl_add_u64 v[40:41], v[40:41], 0, 64
	global_load_dwordx4 v[76:79], v[32:33], off
	global_load_dwordx4 v[80:83], v[34:35], off
	global_load_dwordx4 v[84:87], v[36:37], off
	global_load_dwordx4 v[88:91], v[38:39], off
	global_load_dwordx4 v[92:95], v[40:41], off
	v_lshl_add_u64 v[32:33], v[32:33], 0, 64
	v_lshl_add_u64 v[34:35], v[34:35], 0, 64
	v_lshl_add_u64 v[36:37], v[36:37], 0, 64
	v_lshl_add_u64 v[38:39], v[38:39], 0, 64
	v_lshl_add_u64 v[40:41], v[40:41], 0, 64
	global_load_dwordx4 v[96:99], v[32:33], off
	global_load_dwordx4 v[100:103], v[34:35], off
	global_load_dwordx4 v[104:107], v[36:37], off
	global_load_dwordx4 v[108:111], v[38:39], off
	global_load_dwordx4 v[112:115], v[40:41], off
	v_lshl_add_u64 v[32:33], v[32:33], 0, 64
	v_lshl_add_u64 v[34:35], v[34:35], 0, 64
	v_lshl_add_u64 v[36:37], v[36:37], 0, 64
	v_lshl_add_u64 v[38:39], v[38:39], 0, 64
	v_lshl_add_u64 v[40:41], v[40:41], 0, 64
	global_load_dwordx4 v[116:119], v[32:33], off
	global_load_dwordx4 v[120:123], v[34:35], off
	global_load_dwordx4 v[124:127], v[36:37], off
	global_load_dwordx4 v[128:131], v[38:39], off
	global_load_dwordx4 v[132:135], v[40:41], off
	v_lshl_add_u64 v[32:33], v[32:33], 0, 64
	v_lshl_add_u64 v[34:35], v[34:35], 0, 64
	v_lshl_add_u64 v[36:37], v[36:37], 0, 64
	v_lshl_add_u64 v[38:39], v[38:39], 0, 64
	v_lshl_add_u64 v[40:41], v[40:41], 0, 64
.Ltr_loop:
	s_cmp_lt_u32 s101, 4
	s_cbranch_scc1 .Ltr_drain0
	s_waitcnt vmcnt(15)
	s_branch .Ltr_go0

; __device__ __forceinline__ void tail_resid(const bf16* __restrict__ A, const bf16* __restrict__ Bt, int K, unsigned char* ws, int slot, float amul, LAS unsigned char* lds, int lane, int wave) {
;     ...
;         for (int k0 = 0; k0 < kw; k0 += 32) {
;             const bf16x8 af = *(const bf16x8*)(ap + k0);
; #pragma unroll
;             for (int t = 0; t < 4; ++t) { const bf16x8 bf = *(const bf16x8*)(bp + (size_t)(16 * t) * K + k0); acc[t] = __builtin_amdgcn_mfma_f32_16x16x32_bf16(bf, af, acc[t], 0, 0, 0); }
;         }
.Ltr_go0:
	v_mfma_f32_16x16x32_bf16 v[14:17], v[60:63], v[56:59], v[14:17]
	v_mfma_f32_16x16x32_bf16 v[10:13], v[64:67], v[56:59], v[10:13]
	v_mfma_f32_16x16x32_bf16 v[6:9], v[68:71], v[56:59], v[6:9]
	v_mfma_f32_16x16x32_bf16 v[2:5], v[72:75], v[56:59], v[2:5]
	s_cmp_lt_i32 s15, 1
	s_cbranch_scc1 .Ltr_noiss0
	global_load_dwordx4 v[56:59], v[32:33], off
	global_load_dwordx4 v[60:63], v[34:35], off
	global_load_dwordx4 v[64:67], v[36:37], off
	global_load_dwordx4 v[68:71], v[38:39], off
	global_load_dwordx4 v[72:75], v[40:41], off
	v_lshl_add_u64 v[32:33], v[32:33], 0, 64
	v_lshl_add_u64 v[34:35], v[34:35], 0, 64
	v_lshl_add_u64 v[36:37], v[36:37], 0, 64
	v_lshl_add_u64 v[38:39], v[38:39], 0, 64
	v_lshl_add_u64 v[40:41], v[40:41], 0, 64
	s_add_i32 s15, s15, -1
.Ltr_noiss0:
	s_add_i32 s101, s101, -1
	s_cmp_eq_u32 s101, 0
	s_cbranch_scc1 .Ltr_done
	s_cmp_lt_u32 s101, 4
	s_cbranch_scc1 .Ltr_drain1
	s_waitcnt vmcnt(15)
	s_branch .Ltr_go1

; __device__ __forceinline__ void tail_resid(const bf16* __restrict__ A, const bf16* __restrict__ Bt, int K, unsigned char* ws, int slot, float amul, LAS unsigned char* lds, int lane, int wave) {
;     ...
;         for (int k0 = 0; k0 < kw; k0 += 32) {
;             const bf16x8 af = *(const bf16x8*)(ap + k0);
; #pragma unroll
;             for (int t = 0; t < 4; ++t) { const bf16x8 bf = *(const bf16x8*)(bp + (size_t)(16 * t) * K + k0); acc[t] = __builtin_amdgcn_mfma_f32_16x16x32_bf16(bf, af, acc[t], 0, 0, 0); }
;         }
.Ltr_go1:
	v_mfma_f32_16x16x32_bf16 v[14:17], v[80:83], v[76:79], v[14:17]
	v_mfma_f32_16x16x32_bf16 v[10:13], v[84:87], v[76:79], v[10:13]
	v_mfma_f32_16x16x32_bf16 v[6:9], v[88:91], v[76:79], v[6:9]
	v_mfma_f32_16x16x32_bf16 v[2:5], v[92:95], v[76:79], v[2:5]
	s_cmp_lt_i32 s15, 1
	s_cbranch_scc1 .Ltr_noiss1
	global_load_dwordx4 v[76:79], v[32:33], off
	global_load_dwordx4 v[80:83], v[34:35], off
	global_load_dwordx4 v[84:87], v[36:37], off
	global_load_dwordx4 v[88:91], v[38:39], off
	global_load_dwordx4 v[92:95], v[40:41], off
	v_lshl_add_u64 v[32:33], v[32:33], 0, 64
	v_lshl_add_u64 v[34:35], v[34:35], 0, 64
	v_lshl_add_u64 v[36:37], v[36:37], 0, 64
	v_lshl_add_u64 v[38:39], v[38:39], 0, 64
	v_lshl_add_u64 v[40:41], v[40:41], 0, 64
	s_add_i32 s15, s15, -1

; __device__ __forceinline__ void tail_resid(const bf16* __restrict__ A, const bf16* __restrict__ Bt, int K, unsigned char* ws, int slot, float amul, LAS unsigned char* lds, int lane, int wave) {
;     ...
;         for (int k0 = 0; k0 < kw; k0 += 32) {
;             const bf16x8 af = *(const bf16x8*)(ap + k0);
; #pragma unroll
;             for (int t = 0; t < 4; ++t) { const bf16x8 bf = *(const bf16x8*)(bp + (size_t)(16 * t) * K + k0); acc[t] = __builtin_amdgcn_mfma_f32_16x16x32_bf16(bf, af, acc[t], 0, 0, 0); }
;         }
.Ltr_go2:
	v_mfma_f32_16x16x32_bf16 v[14:17], v[100:103], v[96:99], v[14:17]
	v_mfma_f32_16x16x32_bf16 v[10:13], v[104:107], v[96:99], v[10:13]
	v_mfma_f32_16x16x32_bf16 v[6:9], v[108:111], v[96:99], v[6:9]
	v_mfma_f32_16x16x32_bf16 v[2:5], v[112:115], v[96:99], v[2:5]
	s_cmp_lt_i32 s15, 1
	s_cbranch_scc1 .Ltr_noiss2
	global_load_dwordx4 v[96:99], v[32:33], off
	global_load_dwordx4 v[100:103], v[34:35], off
	global_load_dwordx4 v[104:107], v[36:37], off
	global_load_dwordx4 v[108:111], v[38:39], off
	global_load_dwordx4 v[112:115], v[40:41], off
	v_lshl_add_u64 v[32:33], v[32:33], 0, 64
	v_lshl_add_u64 v[34:35], v[34:35], 0, 64
	v_lshl_add_u64 v[36:37], v[36:37], 0, 64
	v_lshl_add_u64 v[38:39], v[38:39], 0, 64
	v_lshl_add_u64 v[40:41], v[40:41], 0, 64
	s_add_i32 s15, s15, -1

; #define LAS __attribute__((address_space(3)))
; __device__ __forceinline__ void tail_resid(const bf16* __restrict__ A, const bf16* __restrict__ Bt, int K, unsigned char* ws, int slot, float amul, LAS unsigned char* lds, int lane, int wave) {
;     ...
;         for (int k0 = 0; k0 < kw; k0 += 32) {
;             const bf16x8 af = *(const bf16x8*)(ap + k0);
; #pragma unroll
;             for (int t = 0; t < 4; ++t) { const bf16x8 bf = *(const bf16x8*)(bp + (size_t)(16 * t) * K + k0); acc[t] = __builtin_amdgcn_mfma_f32_16x16x32_bf16(bf, af, acc[t], 0, 0, 0); }
;         }
;         __syncthreads();
; #pragma unroll
;         for (int t = 0; t < 4; ++t) *(LAS f32x4*)(lds + ((wave * 4 + t) * 64 + lane) * 16) = acc[t];
;         __syncthreads();
;         if (wave == 0) {
; #pragma unroll
;             for (int t = 0; t < 4; ++t) { f32x4 s = acc[t];
; #pragma unroll
;                 for (int w = 1; w < 8; ++w) s += *(LAS f32x4*)(lds + ((w * 4 + t) * 64 + lane) * 16);
;                 acc[t] = s; }
.Ltr_go3:
	v_mfma_f32_16x16x32_bf16 v[14:17], v[120:123], v[116:119], v[14:17]
	v_mfma_f32_16x16x32_bf16 v[10:13], v[124:127], v[116:119], v[10:13]
	v_mfma_f32_16x16x32_bf16 v[6:9], v[128:131], v[116:119], v[6:9]
	v_mfma_f32_16x16x32_bf16 v[2:5], v[132:135], v[116:119], v[2:5]
	s_cmp_lt_i32 s15, 1
	s_cbranch_scc1 .Ltr_noiss3
	global_load_dwordx4 v[116:119], v[32:33], off
	global_load_dwordx4 v[120:123], v[34:35], off
	global_load_dwordx4 v[124:127], v[36:37], off
	global_load_dwordx4 v[128:131], v[38:39], off
	global_load_dwordx4 v[132:135], v[40:41], off
	v_lshl_add_u64 v[32:33], v[32:33], 0, 64
	v_lshl_add_u64 v[34:35], v[34:35], 0, 64
	v_lshl_add_u64 v[36:37], v[36:37], 0, 64
	v_lshl_add_u64 v[38:39], v[38:39], 0, 64
	v_lshl_add_u64 v[40:41], v[40:41], 0, 64
	s_add_i32 s15, s15, -1
.Ltr_noiss3:
	s_add_i32 s101, s101, -1
	s_cmp_eq_u32 s101, 0
	s_cbranch_scc1 .Ltr_done
	s_branch .Ltr_loop
.Ltr_done:
	v_add_u32_e32 v0, s17, v46
	s_and_b64 vcc, exec, s[0:1]
	s_waitcnt lgkmcnt(0)
	s_barrier
	ds_write_b128 v0, v[14:17]
	ds_write_b128 v0, v[10:13] offset:1024
	ds_write_b128 v0, v[6:9] offset:2048
	ds_write_b128 v0, v[2:5] offset:3072
	s_waitcnt lgkmcnt(0)
	s_barrier
	s_cbranch_vccz .LBB0_1403
	v_add_u32_e32 v0, 0, v46
	ds_read_b128 v[32:35], v0 offset:4096
	s_lshl_b32 s94, s14, 1
	v_mov_b32_e32 v29, v1
	s_andn2_b64 vcc, exec, s[2:3]
	s_waitcnt lgkmcnt(0)
	v_pk_add_f32 v[34:35], v[16:17], v[34:35]
	v_pk_add_f32 v[32:33], v[14:15], v[32:33]
	ds_read_b128 v[14:17], v0 offset:8192
	s_waitcnt lgkmcnt(0)
	v_pk_add_f32 v[34:35], v[34:35], v[16:17]
	v_pk_add_f32 v[32:33], v[32:33], v[14:15]
	ds_read_b128 v[14:17], v0 offset:12288
	s_waitcnt lgkmcnt(0)
	v_pk_add_f32 v[34:35], v[34:35], v[16:17]
	v_pk_add_f32 v[32:33], v[32:33], v[14:15]
	ds_read_b128 v[14:17], v0 offset:16384
	s_waitcnt lgkmcnt(0)
	v_pk_add_f32 v[34:35], v[34:35], v[16:17]
	v_pk_add_f32 v[32:33], v[32:33], v[14:15]
	ds_read_b128 v[14:17], v0 offset:20480
	s_waitcnt lgkmcnt(0)
	v_pk_add_f32 v[34:35], v[34:35], v[16:17]
	v_pk_add_f32 v[32:33], v[32:33], v[14:15]
	ds_read_b128 v[14:17], v0 offset:24576
	s_waitcnt lgkmcnt(0)
	v_pk_add_f32 v[34:35], v[34:35], v[16:17]
	v_pk_add_f32 v[32:33], v[32:33], v[14:15]
	ds_read_b128 v[14:17], v0 offset:28672
	s_waitcnt lgkmcnt(0)
	v_pk_add_f32 v[34:35], v[34:35], v[16:17]
	v_pk_add_f32 v[36:37], v[32:33], v[14:15]
	ds_read_b128 v[14:17], v0 offset:5120
	s_waitcnt lgkmcnt(0)
	v_pk_add_f32 v[16:17], v[12:13], v[16:17]
	v_pk_add_f32 v[14:15], v[10:11], v[14:15]
	ds_read_b128 v[10:13], v0 offset:9216
	s_waitcnt lgkmcnt(0)
	v_pk_add_f32 v[16:17], v[16:17], v[12:13]
	v_pk_add_f32 v[14:15], v[14:15], v[10:11]
	ds_read_b128 v[10:13], v0 offset:13312
	s_waitcnt lgkmcnt(0)
	v_pk_add_f32 v[16:17], v[16:17], v[12:13]
	v_pk_add_f32 v[14:15], v[14:15], v[10:11]
	ds_read_b128 v[10:13], v0 offset:17408
	s_waitcnt lgkmcnt(0)
	v_pk_add_f32 v[16:17], v[16:17], v[12:13]
	v_pk_add_f32 v[14:15], v[14:15], v[10:11]
	ds_read_b128 v[10:13], v0 offset:21504
	s_waitcnt lgkmcnt(0)
	v_pk_add_f32 v[16:17], v[16:17], v[12:13]
	v_pk_add_f32 v[14:15], v[14:15], v[10:11]
	ds_read_b128 v[10:13], v0 offset:25600
	s_waitcnt lgkmcnt(0)
	v_pk_add_f32 v[16:17], v[16:17], v[12:13]
	v_pk_add_f32 v[14:15], v[14:15], v[10:11]
	ds_read_b128 v[10:13], v0 offset:29696
	s_waitcnt lgkmcnt(0)
	v_pk_add_f32 v[16:17], v[16:17], v[12:13]
	v_pk_add_f32 v[32:33], v[14:15], v[10:11]
	ds_read_b128 v[10:13], v0 offset:6144
	s_waitcnt lgkmcnt(0)
	v_pk_add_f32 v[12:13], v[8:9], v[12:13]
	v_pk_add_f32 v[10:11], v[6:7], v[10:11]
	ds_read_b128 v[6:9], v0 offset:10240
	s_waitcnt lgkmcnt(0)
	v_pk_add_f32 v[12:13], v[12:13], v[8:9]
	v_pk_add_f32 v[10:11], v[10:11], v[6:7]
	ds_read_b128 v[6:9], v0 offset:14336
	s_waitcnt lgkmcnt(0)
	v_pk_add_f32 v[12:13], v[12:13], v[8:9]
	v_pk_add_f32 v[10:11], v[10:11], v[6:7]
	ds_read_b128 v[6:9], v0 offset:18432
	s_waitcnt lgkmcnt(0)
	v_pk_add_f32 v[12:13], v[12:13], v[8:9]
	v_pk_add_f32 v[10:11], v[10:11], v[6:7]
	ds_read_b128 v[6:9], v0 offset:22528
	s_waitcnt lgkmcnt(0)
	v_pk_add_f32 v[12:13], v[12:13], v[8:9]
	v_pk_add_f32 v[10:11], v[10:11], v[6:7]
	ds_read_b128 v[6:9], v0 offset:26624
	s_waitcnt lgkmcnt(0)
; #define LAS __attribute__((address_space(3)))
; __device__ __forceinline__ f32x4 ld_bf4(const bf16* q) { const v2u w = *(const v2u*)q; return (f32x4){bf_lo(w.x), bf_hi(w.x), bf_lo(w.y), bf_hi(w.y)}; }
; __device__ __forceinline__ void st_bf4(bf16* q, const f32x4 v) { v2u w; w.x = cvt_pk_bf16(v.x, v.y); w.y = cvt_pk_bf16(v.z, v.w); *(v2u*)q = w; }
; __device__ __forceinline__ float shfl_xor_l(float v, int m, int lane) { return __int_as_float(__builtin_amdgcn_ds_bpermute((lane ^ m) << 2, __float_as_int(v))); }
; __device__ __forceinline__ void tail_resid(const bf16* __restrict__ A, const bf16* __restrict__ Bt, int K, unsigned char* ws, int slot, float amul, LAS unsigned char* lds, int lane, int wave) {
;     ...
;         if (wave == 0) {
; #pragma unroll
;             for (int t = 0; t < 4; ++t) { f32x4 s = acc[t];
; #pragma unroll
;                 for (int w = 1; w < 8; ++w) s += *(LAS f32x4*)(lds + ((w * 4 + t) * 64 + lane) * 16);
;                 acc[t] = s; }
;             const int row = MT0 + 16 * rs + fr;
;             bf16* xb = (bf16*)(ws + WS_XB) + (size_t)row * D + 64 * cs + 4 * fq;
;             float ssq = 0.f;
; #pragma unroll
;             for (int t = 0; t < 4; ++t) { const f32x4 v = ld_bf4(xb + 16 * t) + acc[t] * amul; st_bf4(xb + 16 * t, v);
;                 if (slot >= 0) ssq += (v.x * v.x + v.y * v.y) + (v.z * v.z + v.w * v.w); }
;             if (slot >= 0) { ssq += shfl_xor_l(ssq, 16, lane); ssq += shfl_xor_l(ssq, 32, lane); if (fq == 0) ((float*)(ws + WS_SS))[((size_t)slot * M + row) * 16 + cs] = ssq; }
	v_pk_add_f32 v[12:13], v[12:13], v[8:9]
	v_pk_add_f32 v[10:11], v[10:11], v[6:7]
	ds_read_b128 v[6:9], v0 offset:30720
	s_waitcnt lgkmcnt(0)
	v_pk_add_f32 v[12:13], v[12:13], v[8:9]
	v_pk_add_f32 v[14:15], v[10:11], v[6:7]
	ds_read_b128 v[6:9], v0 offset:7168
	s_waitcnt lgkmcnt(0)
	v_pk_add_f32 v[8:9], v[4:5], v[8:9]
	v_pk_add_f32 v[6:7], v[2:3], v[6:7]
	ds_read_b128 v[2:5], v0 offset:11264
	s_waitcnt lgkmcnt(0)
	v_pk_add_f32 v[8:9], v[8:9], v[4:5]
	v_pk_add_f32 v[6:7], v[6:7], v[2:3]
	ds_read_b128 v[2:5], v0 offset:15360
	s_waitcnt lgkmcnt(0)
	v_pk_add_f32 v[8:9], v[8:9], v[4:5]
	v_pk_add_f32 v[6:7], v[6:7], v[2:3]
	ds_read_b128 v[2:5], v0 offset:19456
	s_waitcnt lgkmcnt(0)
	v_pk_add_f32 v[8:9], v[8:9], v[4:5]
	v_pk_add_f32 v[6:7], v[6:7], v[2:3]
	ds_read_b128 v[2:5], v0 offset:23552
	s_waitcnt lgkmcnt(0)
	v_pk_add_f32 v[8:9], v[8:9], v[4:5]
	v_pk_add_f32 v[6:7], v[6:7], v[2:3]
	ds_read_b128 v[2:5], v0 offset:27648
	s_waitcnt lgkmcnt(0)
	v_pk_add_f32 v[8:9], v[8:9], v[4:5]
	v_pk_add_f32 v[6:7], v[6:7], v[2:3]
	ds_read_b128 v[2:5], v0 offset:31744
	s_waitcnt lgkmcnt(0)
	v_pk_add_f32 v[2:3], v[6:7], v[2:3]
	v_lshlrev_b64 v[6:7], 11, v[30:31]
	v_lshl_add_u64 v[6:7], s[90:91], 0, v[6:7]
	v_lshl_add_u64 v[6:7], v[6:7], 0, s[94:95]
	v_lshl_add_u64 v[10:11], v[6:7], 0, v[28:29]
	global_load_dwordx2 v[6:7], v[10:11], off
	v_pk_add_f32 v[4:5], v[8:9], v[4:5]
	s_waitcnt vmcnt(0)
	v_lshlrev_b32_e32 v8, 16, v6
	v_and_b32_e32 v9, 0xffff0000, v6
	v_lshlrev_b32_e32 v6, 16, v7
	v_and_b32_e32 v7, 0xffff0000, v7
	v_pk_add_f32 v[6:7], v[34:35], v[6:7]
	v_pk_add_f32 v[8:9], v[36:37], v[8:9]
	v_cvt_pk_bf16_f32 v35, v6, v7
	s_nop 0
	v_cvt_pk_bf16_f32 v34, v8, v9
	global_store_dwordx2 v[10:11], v[34:35], off
	global_load_dwordx2 v[34:35], v[10:11], off offset:32
	s_waitcnt vmcnt(0)
	v_lshlrev_b32_e32 v36, 16, v34
	v_and_b32_e32 v37, 0xffff0000, v34
	v_lshlrev_b32_e32 v34, 16, v35
	v_and_b32_e32 v35, 0xffff0000, v35
	v_pk_add_f32 v[16:17], v[16:17], v[34:35]
	v_pk_add_f32 v[32:33], v[32:33], v[36:37]
	v_cvt_pk_bf16_f32 v35, v16, v17
	s_nop 0
	v_cvt_pk_bf16_f32 v34, v32, v33
	global_store_dwordx2 v[10:11], v[34:35], off offset:32
	global_load_dwordx2 v[34:35], v[10:11], off offset:64
	s_waitcnt vmcnt(0)
	v_lshlrev_b32_e32 v36, 16, v34
	v_and_b32_e32 v37, 0xffff0000, v34
	v_lshlrev_b32_e32 v34, 16, v35
	v_and_b32_e32 v35, 0xffff0000, v35
	v_pk_add_f32 v[12:13], v[12:13], v[34:35]
	v_pk_add_f32 v[14:15], v[14:15], v[36:37]
	v_cvt_pk_bf16_f32 v35, v12, v13
	s_nop 0
	v_cvt_pk_bf16_f32 v34, v14, v15
	global_store_dwordx2 v[10:11], v[34:35], off offset:64
	global_load_dwordx2 v[34:35], v[10:11], off offset:96
	s_waitcnt vmcnt(0)
	v_lshlrev_b32_e32 v36, 16, v34
	v_and_b32_e32 v37, 0xffff0000, v34
	v_lshlrev_b32_e32 v34, 16, v35
	v_and_b32_e32 v35, 0xffff0000, v35
	v_pk_add_f32 v[4:5], v[4:5], v[34:35]
	v_pk_add_f32 v[2:3], v[2:3], v[36:37]
	v_cvt_pk_bf16_f32 v35, v4, v5
	s_nop 0
	v_cvt_pk_bf16_f32 v34, v2, v3
	global_store_dwordx2 v[10:11], v[34:35], off offset:96
	s_cbranch_vccnz .LBB0_1403
	v_mul_f32_e32 v0, v9, v9
	v_mul_f32_e32 v7, v7, v7
	v_fmac_f32_e32 v0, v8, v8
	v_fmac_f32_e32 v7, v6, v6
	v_add_f32_e32 v0, v0, v7
	v_mul_f32_e32 v6, v33, v33
	v_mul_f32_e32 v7, v17, v17
	v_fmac_f32_e32 v6, v32, v32
	v_fmac_f32_e32 v7, v16, v16
	v_add_f32_e32 v6, v6, v7
	v_add_f32_e32 v0, v0, v6
	v_mul_f32_e32 v6, v15, v15
	v_mul_f32_e32 v7, v13, v13
	v_mul_f32_e32 v3, v3, v3
	v_fmac_f32_e32 v6, v14, v14
	v_fmac_f32_e32 v7, v12, v12
	v_fmac_f32_e32 v3, v2, v2
	v_mul_f32_e32 v2, v5, v5
	v_add_f32_e32 v6, v6, v7
	v_fmac_f32_e32 v2, v4, v4
	v_add_f32_e32 v0, v0, v6
	v_add_f32_e32 v2, v3, v2
	v_add_f32_e32 v0, v0, v2
	ds_bpermute_b32 v2, v44, v0
	s_waitcnt lgkmcnt(0)
	v_add_f32_e32 v0, v0, v2
	ds_bpermute_b32 v2, v45, v0
	s_and_saveexec_b64 s[14:15], s[4:5]
	s_cbranch_execz .LBB0_1402
	v_lshl_add_u64 v[4:5], s[6:7], 0, v[30:31]
	v_readlane_b32 s20, v252, 23
	v_lshlrev_b64 v[4:5], 6, v[4:5]
	v_readlane_b32 s21, v252, 24
	s_lshl_b32 s94, s18, 2
	s_waitcnt lgkmcnt(0)
	v_add_f32_e32 v0, v0, v2
	v_lshl_add_u64 v[4:5], s[20:21], 0, v[4:5]
	v_lshl_add_u64 v[4:5], v[4:5], 0, s[94:95]
	global_store_dword v[4:5], v0, off
	s_branch .LBB0_1402
